# out-proj: MFMA operands exchanged (acc quad = 4 rows x 1 col), residual epilogue rewritten with dword accesses 64 B contiguous per 16 lanes, 2-deep row-group pipeline
# speedup vs baseline: 1.0086x; 1.0086x over previous
.LBB0_868:
	s_add_u32 s16, s14, 0xfff80080
	s_addc_u32 s17, s15, -1
	s_add_i32 s64, 0, 0x10000
	s_cmp_eq_u32 s63, 28
	s_cselect_b32 s25, s9, s17
	s_cselect_b32 s24, s90, s16
	s_cselect_b32 s17, s7, s62
	s_cselect_b32 s16, s60, s61
	s_add_i32 s66, 0, 0x14000
	v_add_u32_e32 v110, s64, v161
	v_add_u32_e32 v168, s66, v161
	ds_read_b128 v[98:101], v110
	ds_read_b128 v[102:105], v110 offset:1024
	ds_read_b128 v[106:109], v110 offset:2048
	ds_read_b128 v[110:113], v110 offset:3072
	ds_read_b128 v[152:155], v168
	ds_read_b128 v[156:159], v168 offset:1024
	ds_read_b128 v[164:167], v168 offset:2048
	ds_read_b128 v[168:171], v168 offset:3072
	v_lshl_add_u64 v[176:177], s[14:15], 0, v[148:149]
	s_add_i32 m0, s52, 0xc000
	ds_read_b128 v[172:175], v163
	ds_read_b128 v[190:193], v163 offset:1024
	ds_read_b128 v[194:197], v163 offset:2048
	ds_read_b128 v[198:201], v163 offset:3072
	ds_read_b128 v[202:205], v163 offset:4096
	ds_read_b128 v[206:209], v163 offset:5120
	ds_read_b128 v[230:233], v163 offset:6144
	ds_read_b128 v[234:237], v163 offset:7168
	global_load_lds_dwordx4 v[176:177], off
	v_lshl_add_u64 v[176:177], s[14:15], 0, v[150:151]
	s_add_i32 m0, s52, 0xe000
	s_nop 0
	global_load_lds_dwordx4 v[176:177], off
	s_waitcnt vmcnt(8)
	s_waitcnt lgkmcnt(0)
	s_barrier
	s_setprio 1
	s_waitcnt lgkmcnt(0)
	v_mfma_f32_16x16x32_bf16 v[142:145], v[172:175], v[98:101], v[142:145]
	v_mfma_f32_16x16x32_bf16 v[138:141], v[172:175], v[106:109], v[138:141]
	v_mfma_f32_16x16x32_bf16 v[134:137], v[194:197], v[98:101], v[134:137]
	v_mfma_f32_16x16x32_bf16 v[130:133], v[194:197], v[106:109], v[130:133]
	v_mfma_f32_16x16x32_bf16 v[94:97], v[202:205], v[98:101], v[94:97]
	v_mfma_f32_16x16x32_bf16 v[90:93], v[202:205], v[106:109], v[90:93]
	v_mfma_f32_16x16x32_bf16 v[86:89], v[230:233], v[98:101], v[86:89]
	v_mfma_f32_16x16x32_bf16 v[82:85], v[230:233], v[106:109], v[82:85]
	v_mfma_f32_16x16x32_bf16 v[142:145], v[190:193], v[102:105], v[142:145]
	v_mfma_f32_16x16x32_bf16 v[138:141], v[190:193], v[110:113], v[138:141]
	v_mfma_f32_16x16x32_bf16 v[134:137], v[198:201], v[102:105], v[134:137]
	v_mfma_f32_16x16x32_bf16 v[130:133], v[198:201], v[110:113], v[130:133]
	v_mfma_f32_16x16x32_bf16 v[94:97], v[206:209], v[102:105], v[94:97]
	v_mfma_f32_16x16x32_bf16 v[90:93], v[206:209], v[110:113], v[90:93]
	v_mfma_f32_16x16x32_bf16 v[86:89], v[234:237], v[102:105], v[86:89]
	v_mfma_f32_16x16x32_bf16 v[82:85], v[234:237], v[110:113], v[82:85]
	s_setprio 0
	s_setprio 1
	v_mfma_f32_16x16x32_bf16 v[126:129], v[172:175], v[152:155], v[126:129]
	v_mfma_f32_16x16x32_bf16 v[122:125], v[172:175], v[164:167], v[122:125]
	v_mfma_f32_16x16x32_bf16 v[118:121], v[194:197], v[152:155], v[118:121]
	v_mfma_f32_16x16x32_bf16 v[114:117], v[194:197], v[164:167], v[114:117]
	v_mfma_f32_16x16x32_bf16 v[78:81], v[202:205], v[152:155], v[78:81]
	v_mfma_f32_16x16x32_bf16 v[74:77], v[202:205], v[164:167], v[74:77]
	v_mfma_f32_16x16x32_bf16 v[70:73], v[230:233], v[152:155], v[70:73]
	v_mfma_f32_16x16x32_bf16 v[66:69], v[230:233], v[164:167], v[66:69]
	v_mfma_f32_16x16x32_bf16 v[126:129], v[190:193], v[156:159], v[126:129]
	v_mfma_f32_16x16x32_bf16 v[122:125], v[190:193], v[168:171], v[122:125]
	v_mfma_f32_16x16x32_bf16 v[118:121], v[198:201], v[156:159], v[118:121]
	v_mfma_f32_16x16x32_bf16 v[114:117], v[198:201], v[168:171], v[114:117]
	v_mfma_f32_16x16x32_bf16 v[78:81], v[206:209], v[156:159], v[78:81]
	v_mfma_f32_16x16x32_bf16 v[74:77], v[206:209], v[168:171], v[74:77]
	v_mfma_f32_16x16x32_bf16 v[70:73], v[234:237], v[156:159], v[70:73]
	v_mfma_f32_16x16x32_bf16 v[66:69], v[234:237], v[168:171], v[66:69]
	s_setprio 0
	s_barrier
	s_add_i32 s64, s64, s37
	v_lshl_add_u64 v[176:177], s[16:17], 0, v[32:33]
	s_mov_b32 m0, s64
	ds_read_b128 v[172:175], v163 offset:16384
	ds_read_b128 v[190:193], v163 offset:17408
	ds_read_b128 v[194:197], v163 offset:18432
	ds_read_b128 v[198:201], v163 offset:19456
	ds_read_b128 v[202:205], v163 offset:20480
	ds_read_b128 v[206:209], v163 offset:21504
	ds_read_b128 v[230:233], v163 offset:22528
	ds_read_b128 v[234:237], v163 offset:23552
	global_load_lds_dwordx4 v[176:177], off
	s_add_i32 m0, s64, 0x2000
	s_add_u32 s64, s16, 0x80000
	v_lshl_add_u64 v[238:239], s[16:17], 0, v[146:147]
	s_addc_u32 s65, s17, 0
	s_add_i32 s66, s66, s37
	global_load_lds_dwordx4 v[238:239], off
	v_lshl_add_u64 v[240:241], s[64:65], 0, v[32:33]
	s_mov_b32 m0, s66
	v_lshl_add_u64 v[242:243], s[24:25], 0, v[146:147]
	global_load_lds_dwordx4 v[240:241], off
	v_lshl_add_u64 v[240:241], s[64:65], 0, v[146:147]
	s_add_i32 m0, s66, 0x2000
	s_nop 0
	global_load_lds_dwordx4 v[240:241], off
	v_lshl_add_u64 v[240:241], s[24:25], 0, v[32:33]
	s_mov_b32 m0, s52
	s_nop 0
	global_load_lds_dwordx4 v[240:241], off
	s_mov_b32 m0, s53
	s_nop 0
	global_load_lds_dwordx4 v[242:243], off
	s_waitcnt vmcnt(8)
	s_waitcnt lgkmcnt(0)
	s_barrier
	s_setprio 1
	s_waitcnt lgkmcnt(0)
	v_mfma_f32_16x16x32_bf16 v[62:65], v[172:175], v[98:101], v[62:65]
	v_mfma_f32_16x16x32_bf16 v[58:61], v[172:175], v[106:109], v[58:61]
	v_mfma_f32_16x16x32_bf16 v[54:57], v[194:197], v[98:101], v[54:57]
	v_mfma_f32_16x16x32_bf16 v[50:53], v[194:197], v[106:109], v[50:53]
	v_mfma_f32_16x16x32_bf16 v[28:31], v[202:205], v[98:101], v[28:31]
	v_mfma_f32_16x16x32_bf16 v[24:27], v[202:205], v[106:109], v[24:27]
	v_mfma_f32_16x16x32_bf16 v[20:23], v[230:233], v[98:101], v[20:23]
	v_mfma_f32_16x16x32_bf16 v[16:19], v[230:233], v[106:109], v[16:19]
	v_mfma_f32_16x16x32_bf16 v[62:65], v[190:193], v[102:105], v[62:65]
	v_mfma_f32_16x16x32_bf16 v[58:61], v[190:193], v[110:113], v[58:61]
	v_mfma_f32_16x16x32_bf16 v[54:57], v[198:201], v[102:105], v[54:57]
	v_mfma_f32_16x16x32_bf16 v[50:53], v[198:201], v[110:113], v[50:53]
	v_mfma_f32_16x16x32_bf16 v[28:31], v[206:209], v[102:105], v[28:31]
	v_mfma_f32_16x16x32_bf16 v[24:27], v[206:209], v[110:113], v[24:27]
	v_mfma_f32_16x16x32_bf16 v[20:23], v[234:237], v[102:105], v[20:23]
	v_mfma_f32_16x16x32_bf16 v[16:19], v[234:237], v[110:113], v[16:19]
	s_setprio 0
	s_setprio 1
	v_mfma_f32_16x16x32_bf16 v[46:49], v[172:175], v[152:155], v[46:49]
	v_mfma_f32_16x16x32_bf16 v[42:45], v[172:175], v[164:167], v[42:45]
	v_mfma_f32_16x16x32_bf16 v[38:41], v[194:197], v[152:155], v[38:41]
	v_mfma_f32_16x16x32_bf16 v[34:37], v[194:197], v[164:167], v[34:37]
	v_mfma_f32_16x16x32_bf16 v[12:15], v[202:205], v[152:155], v[12:15]
	v_mfma_f32_16x16x32_bf16 v[8:11], v[202:205], v[164:167], v[8:11]
	v_mfma_f32_16x16x32_bf16 v[4:7], v[230:233], v[152:155], v[4:7]
	v_mfma_f32_16x16x32_bf16 v[0:3], v[230:233], v[164:167], v[0:3]
	v_mfma_f32_16x16x32_bf16 v[46:49], v[190:193], v[156:159], v[46:49]
	v_mfma_f32_16x16x32_bf16 v[42:45], v[190:193], v[168:171], v[42:45]
	v_mfma_f32_16x16x32_bf16 v[38:41], v[198:201], v[156:159], v[38:41]
	v_mfma_f32_16x16x32_bf16 v[34:37], v[198:201], v[168:171], v[34:37]
	v_mfma_f32_16x16x32_bf16 v[12:15], v[206:209], v[156:159], v[12:15]
	v_mfma_f32_16x16x32_bf16 v[8:11], v[206:209], v[168:171], v[8:11]
	v_mfma_f32_16x16x32_bf16 v[4:7], v[234:237], v[156:159], v[4:7]
	v_mfma_f32_16x16x32_bf16 v[0:3], v[234:237], v[168:171], v[0:3]
	s_setprio 0
	s_barrier
	s_add_i32 s64, 0, 0x18000
	s_add_i32 s65, 0, 0x1c000
	v_add_u32_e32 v110, s64, v161
	v_add_u32_e32 v168, s65, v161
	ds_read_b128 v[98:101], v110
	ds_read_b128 v[102:105], v110 offset:1024
	ds_read_b128 v[106:109], v110 offset:2048
	ds_read_b128 v[110:113], v110 offset:3072
	ds_read_b128 v[152:155], v168
	ds_read_b128 v[156:159], v168 offset:1024
	ds_read_b128 v[164:167], v168 offset:2048
	ds_read_b128 v[168:171], v168 offset:3072
	s_add_u32 s24, s24, 0x80000
	s_addc_u32 s25, s25, 0
	s_mov_b32 m0, s56
	v_lshl_add_u64 v[244:245], s[24:25], 0, v[32:33]
	ds_read_b128 v[172:175], v163 offset:32768
	ds_read_b128 v[190:193], v163 offset:33792
	ds_read_b128 v[194:197], v163 offset:34816
	ds_read_b128 v[198:201], v163 offset:35840
	ds_read_b128 v[202:205], v163 offset:36864
	ds_read_b128 v[206:209], v163 offset:37888
	ds_read_b128 v[230:233], v163 offset:38912
	ds_read_b128 v[234:237], v163 offset:39936
	global_load_lds_dwordx4 v[244:245], off
	v_lshl_add_u64 v[244:245], s[24:25], 0, v[146:147]
	s_mov_b32 m0, s57
	s_nop 0
	global_load_lds_dwordx4 v[244:245], off
	s_waitcnt vmcnt(8)
	s_waitcnt lgkmcnt(0)
	s_barrier
	s_setprio 1
	s_waitcnt lgkmcnt(0)
	v_mfma_f32_16x16x32_bf16 v[142:145], v[172:175], v[98:101], v[142:145]
	v_mfma_f32_16x16x32_bf16 v[138:141], v[172:175], v[106:109], v[138:141]
	v_mfma_f32_16x16x32_bf16 v[134:137], v[194:197], v[98:101], v[134:137]
	v_mfma_f32_16x16x32_bf16 v[130:133], v[194:197], v[106:109], v[130:133]
	v_mfma_f32_16x16x32_bf16 v[94:97], v[202:205], v[98:101], v[94:97]
	v_mfma_f32_16x16x32_bf16 v[90:93], v[202:205], v[106:109], v[90:93]
	v_mfma_f32_16x16x32_bf16 v[86:89], v[230:233], v[98:101], v[86:89]
	v_mfma_f32_16x16x32_bf16 v[82:85], v[230:233], v[106:109], v[82:85]
	v_mfma_f32_16x16x32_bf16 v[142:145], v[190:193], v[102:105], v[142:145]
	v_mfma_f32_16x16x32_bf16 v[138:141], v[190:193], v[110:113], v[138:141]
	v_mfma_f32_16x16x32_bf16 v[134:137], v[198:201], v[102:105], v[134:137]
	v_mfma_f32_16x16x32_bf16 v[130:133], v[198:201], v[110:113], v[130:133]
	v_mfma_f32_16x16x32_bf16 v[94:97], v[206:209], v[102:105], v[94:97]
	v_mfma_f32_16x16x32_bf16 v[90:93], v[206:209], v[110:113], v[90:93]
	v_mfma_f32_16x16x32_bf16 v[86:89], v[234:237], v[102:105], v[86:89]
	v_mfma_f32_16x16x32_bf16 v[82:85], v[234:237], v[110:113], v[82:85]
	s_setprio 0
	s_setprio 1
	v_mfma_f32_16x16x32_bf16 v[126:129], v[172:175], v[152:155], v[126:129]
	v_mfma_f32_16x16x32_bf16 v[122:125], v[172:175], v[164:167], v[122:125]
	v_mfma_f32_16x16x32_bf16 v[118:121], v[194:197], v[152:155], v[118:121]
	v_mfma_f32_16x16x32_bf16 v[114:117], v[194:197], v[164:167], v[114:117]
	v_mfma_f32_16x16x32_bf16 v[78:81], v[202:205], v[152:155], v[78:81]
	v_mfma_f32_16x16x32_bf16 v[74:77], v[202:205], v[164:167], v[74:77]
	v_mfma_f32_16x16x32_bf16 v[70:73], v[230:233], v[152:155], v[70:73]
	v_mfma_f32_16x16x32_bf16 v[66:69], v[230:233], v[164:167], v[66:69]
	v_mfma_f32_16x16x32_bf16 v[126:129], v[190:193], v[156:159], v[126:129]
	v_mfma_f32_16x16x32_bf16 v[122:125], v[190:193], v[168:171], v[122:125]
	v_mfma_f32_16x16x32_bf16 v[118:121], v[198:201], v[156:159], v[118:121]
	v_mfma_f32_16x16x32_bf16 v[114:117], v[198:201], v[168:171], v[114:117]
	v_mfma_f32_16x16x32_bf16 v[78:81], v[206:209], v[156:159], v[78:81]
	v_mfma_f32_16x16x32_bf16 v[74:77], v[206:209], v[168:171], v[74:77]
	v_mfma_f32_16x16x32_bf16 v[70:73], v[234:237], v[156:159], v[70:73]
	v_mfma_f32_16x16x32_bf16 v[66:69], v[234:237], v[168:171], v[66:69]
	s_setprio 0
	s_barrier
	s_add_i32 s24, s64, s37
	v_lshl_add_u64 v[176:177], v[176:177], 0, s[84:85]
	s_mov_b32 m0, s24
	ds_read_b128 v[172:175], v163 offset:49152
	ds_read_b128 v[190:193], v163 offset:50176
	ds_read_b128 v[194:197], v163 offset:51200
	ds_read_b128 v[198:201], v163 offset:52224
	ds_read_b128 v[202:205], v163 offset:53248
	ds_read_b128 v[206:209], v163 offset:54272
	ds_read_b128 v[230:233], v163 offset:55296
	ds_read_b128 v[234:237], v163 offset:56320
	global_load_lds_dwordx4 v[176:177], off
	s_add_i32 m0, s24, 0x2000
	s_add_u32 s16, s16, 0x80080
	v_lshl_add_u64 v[176:177], v[238:239], 0, s[84:85]
	s_addc_u32 s17, s17, 0
	s_add_i32 s24, s65, s37
	global_load_lds_dwordx4 v[176:177], off
	v_lshl_add_u64 v[176:177], s[16:17], 0, v[32:33]
	s_mov_b32 m0, s24
	s_nop 0
	global_load_lds_dwordx4 v[176:177], off
	v_lshl_add_u64 v[176:177], s[16:17], 0, v[146:147]
	s_add_i32 m0, s24, 0x2000
	s_nop 0
	global_load_lds_dwordx4 v[176:177], off
	v_lshl_add_u64 v[176:177], v[240:241], 0, s[84:85]
	s_mov_b32 m0, s86
	s_nop 0
	global_load_lds_dwordx4 v[176:177], off
	v_lshl_add_u64 v[176:177], v[242:243], 0, s[84:85]
	s_mov_b32 m0, s87
	s_nop 0
	global_load_lds_dwordx4 v[176:177], off
	s_waitcnt vmcnt(8)
	s_waitcnt lgkmcnt(0)
	s_barrier
	s_setprio 1
	s_waitcnt lgkmcnt(0)
	v_mfma_f32_16x16x32_bf16 v[62:65], v[172:175], v[98:101], v[62:65]
	v_mfma_f32_16x16x32_bf16 v[58:61], v[172:175], v[106:109], v[58:61]
	v_mfma_f32_16x16x32_bf16 v[54:57], v[194:197], v[98:101], v[54:57]
	v_mfma_f32_16x16x32_bf16 v[50:53], v[194:197], v[106:109], v[50:53]
	v_mfma_f32_16x16x32_bf16 v[28:31], v[202:205], v[98:101], v[28:31]
	v_mfma_f32_16x16x32_bf16 v[24:27], v[202:205], v[106:109], v[24:27]
	v_mfma_f32_16x16x32_bf16 v[20:23], v[230:233], v[98:101], v[20:23]
	v_mfma_f32_16x16x32_bf16 v[16:19], v[230:233], v[106:109], v[16:19]
	v_mfma_f32_16x16x32_bf16 v[62:65], v[190:193], v[102:105], v[62:65]
	v_mfma_f32_16x16x32_bf16 v[58:61], v[190:193], v[110:113], v[58:61]
	v_mfma_f32_16x16x32_bf16 v[54:57], v[198:201], v[102:105], v[54:57]
	v_mfma_f32_16x16x32_bf16 v[50:53], v[198:201], v[110:113], v[50:53]
	v_mfma_f32_16x16x32_bf16 v[28:31], v[206:209], v[102:105], v[28:31]
	v_mfma_f32_16x16x32_bf16 v[24:27], v[206:209], v[110:113], v[24:27]
	v_mfma_f32_16x16x32_bf16 v[20:23], v[234:237], v[102:105], v[20:23]
	v_mfma_f32_16x16x32_bf16 v[16:19], v[234:237], v[110:113], v[16:19]
	s_setprio 0
	s_setprio 1
	v_mfma_f32_16x16x32_bf16 v[46:49], v[172:175], v[152:155], v[46:49]
	v_mfma_f32_16x16x32_bf16 v[42:45], v[172:175], v[164:167], v[42:45]
	v_mfma_f32_16x16x32_bf16 v[38:41], v[194:197], v[152:155], v[38:41]
	v_mfma_f32_16x16x32_bf16 v[34:37], v[194:197], v[164:167], v[34:37]
	v_mfma_f32_16x16x32_bf16 v[12:15], v[202:205], v[152:155], v[12:15]
	v_mfma_f32_16x16x32_bf16 v[8:11], v[202:205], v[164:167], v[8:11]
	v_mfma_f32_16x16x32_bf16 v[4:7], v[230:233], v[152:155], v[4:7]
	v_mfma_f32_16x16x32_bf16 v[0:3], v[230:233], v[164:167], v[0:3]
	v_mfma_f32_16x16x32_bf16 v[46:49], v[190:193], v[156:159], v[46:49]
	v_mfma_f32_16x16x32_bf16 v[42:45], v[190:193], v[168:171], v[42:45]
	v_mfma_f32_16x16x32_bf16 v[38:41], v[198:201], v[156:159], v[38:41]
	v_mfma_f32_16x16x32_bf16 v[34:37], v[198:201], v[168:171], v[34:37]
	v_mfma_f32_16x16x32_bf16 v[12:15], v[206:209], v[156:159], v[12:15]
	v_mfma_f32_16x16x32_bf16 v[8:11], v[206:209], v[168:171], v[8:11]
	v_mfma_f32_16x16x32_bf16 v[4:7], v[234:237], v[156:159], v[4:7]
	v_mfma_f32_16x16x32_bf16 v[0:3], v[234:237], v[168:171], v[0:3]
	s_setprio 0
	s_barrier
	s_add_i32 s63, s63, 2
	s_add_u32 s14, s14, 0x100
	s_addc_u32 s15, s15, 0
	s_add_u32 s61, s61, 0x100
	s_addc_u32 s62, s62, 0
	s_cmp_gt_u32 s63, 29
	s_cbranch_scc0 .LBB0_868
	s_and_b64 vcc, exec, s[4:5]
	s_cbranch_vccz .LBB0_871
	s_barrier
.LBB0_871:
	s_ashr_i32 s7, s54, 3
	s_mul_hi_i32 s9, s7, 0x6000
	s_mulk_i32 s7, 0x6000
	s_add_u32 s14, s58, s7
	s_addc_u32 s15, s59, s9
	v_readlane_b32 s98, v254, 0
	v_readlane_b32 s99, v254, 1
	s_mov_b64 s[100:101], s[48:49]
	v_and_b32_e32 v152, 15, v210
	v_bfe_u32 v153, v210, 4, 2
	v_lshlrev_b32_e32 v153, 2, v153
	v_sub_u32_e32 v153, v153, v152
	v_add_u32_e32 v154, v160, v153
	v_sub_u32_e32 v155, v162, v153
	v_lshl_add_u32 v154, s54, 8, v154
	v_lshl_add_u32 v155, s55, 8, v155
	v_lshlrev_b32_e32 v155, 2, v155
	v_lshl_add_u32 v164, v154, 13, v155
	v_add_u32_e32 v165, 0x2000, v164
	v_add_u32_e32 v166, 0x4000, v164
	v_add_u32_e32 v167, 0x6000, v164
	global_load_dword v98, v155, s[14:15]
	global_load_dword v100, v155, s[14:15] offset:64
	global_load_dword v102, v155, s[14:15] offset:512
	global_load_dword v104, v155, s[14:15] offset:576
	global_load_dword v190, v164, s[98:99]
	global_load_dword v191, v165, s[98:99]
	global_load_dword v192, v166, s[98:99]
	global_load_dword v193, v167, s[98:99]
	global_load_dword v194, v164, s[98:99] offset:64
	global_load_dword v195, v165, s[98:99] offset:64
	global_load_dword v196, v166, s[98:99] offset:64
	global_load_dword v197, v167, s[98:99] offset:64
	global_load_dword v198, v164, s[98:99] offset:512
	global_load_dword v199, v165, s[98:99] offset:512
	global_load_dword v200, v166, s[98:99] offset:512
	global_load_dword v201, v167, s[98:99] offset:512
	global_load_dword v202, v164, s[98:99] offset:576
	global_load_dword v203, v165, s[98:99] offset:576
	global_load_dword v204, v166, s[98:99] offset:576
	global_load_dword v205, v167, s[98:99] offset:576
	s_add_u32 s98, s98, 0x20000
	s_addc_u32 s99, s99, 0
	global_load_dword v152, v164, s[98:99]
	global_load_dword v153, v165, s[98:99]
	global_load_dword v154, v166, s[98:99]
	global_load_dword v155, v167, s[98:99]
	global_load_dword v156, v164, s[98:99] offset:64
	global_load_dword v157, v165, s[98:99] offset:64
	global_load_dword v158, v166, s[98:99] offset:64
	global_load_dword v159, v167, s[98:99] offset:64
	global_load_dword v106, v164, s[98:99] offset:512
	global_load_dword v107, v165, s[98:99] offset:512
	global_load_dword v108, v166, s[98:99] offset:512
	global_load_dword v109, v167, s[98:99] offset:512
	global_load_dword v110, v164, s[98:99] offset:576
	global_load_dword v111, v165, s[98:99] offset:576
	global_load_dword v112, v166, s[98:99] offset:576
	global_load_dword v113, v167, s[98:99] offset:576
	s_add_u32 s98, s98, 0x20000
	s_addc_u32 s99, s99, 0
	s_waitcnt vmcnt(16)
	v_pk_fma_f32 v[142:143], v[142:143], v[98:99], v[190:191] op_sel_hi:[1,0,1]
	v_pk_fma_f32 v[144:145], v[144:145], v[98:99], v[192:193] op_sel_hi:[1,0,1]
	v_pk_fma_f32 v[138:139], v[138:139], v[100:101], v[194:195] op_sel_hi:[1,0,1]
	v_pk_fma_f32 v[140:141], v[140:141], v[100:101], v[196:197] op_sel_hi:[1,0,1]
	v_pk_fma_f32 v[126:127], v[126:127], v[102:103], v[198:199] op_sel_hi:[1,0,1]
	v_pk_fma_f32 v[128:129], v[128:129], v[102:103], v[200:201] op_sel_hi:[1,0,1]
	v_pk_fma_f32 v[122:123], v[122:123], v[104:105], v[202:203] op_sel_hi:[1,0,1]
	v_pk_fma_f32 v[124:125], v[124:125], v[104:105], v[204:205] op_sel_hi:[1,0,1]
	global_store_dword v164, v142, s[100:101]
	global_store_dword v165, v143, s[100:101]
	global_store_dword v166, v144, s[100:101]
	global_store_dword v167, v145, s[100:101]
	global_store_dword v164, v138, s[100:101] offset:64
	global_store_dword v165, v139, s[100:101] offset:64
	global_store_dword v166, v140, s[100:101] offset:64
	global_store_dword v167, v141, s[100:101] offset:64
	global_store_dword v164, v126, s[100:101] offset:512
	global_store_dword v165, v127, s[100:101] offset:512
	global_store_dword v166, v128, s[100:101] offset:512
	global_store_dword v167, v129, s[100:101] offset:512
	global_store_dword v164, v122, s[100:101] offset:576
	global_store_dword v165, v123, s[100:101] offset:576
	global_store_dword v166, v124, s[100:101] offset:576
	global_store_dword v167, v125, s[100:101] offset:576
	s_add_u32 s100, s100, 0x20000
	s_addc_u32 s101, s101, 0
	global_load_dword v190, v164, s[98:99]
	global_load_dword v191, v165, s[98:99]
	global_load_dword v192, v166, s[98:99]
	global_load_dword v193, v167, s[98:99]
	global_load_dword v194, v164, s[98:99] offset:64
	global_load_dword v195, v165, s[98:99] offset:64
	global_load_dword v196, v166, s[98:99] offset:64
	global_load_dword v197, v167, s[98:99] offset:64
	global_load_dword v198, v164, s[98:99] offset:512
	global_load_dword v199, v165, s[98:99] offset:512
	global_load_dword v200, v166, s[98:99] offset:512
	global_load_dword v201, v167, s[98:99] offset:512
	global_load_dword v202, v164, s[98:99] offset:576
	global_load_dword v203, v165, s[98:99] offset:576
	global_load_dword v204, v166, s[98:99] offset:576
	global_load_dword v205, v167, s[98:99] offset:576
	s_add_u32 s98, s98, 0x20000
	s_addc_u32 s99, s99, 0
	s_waitcnt vmcnt(32)
	v_pk_fma_f32 v[134:135], v[134:135], v[98:99], v[152:153] op_sel_hi:[1,0,1]
	v_pk_fma_f32 v[136:137], v[136:137], v[98:99], v[154:155] op_sel_hi:[1,0,1]
	v_pk_fma_f32 v[130:131], v[130:131], v[100:101], v[156:157] op_sel_hi:[1,0,1]
	v_pk_fma_f32 v[132:133], v[132:133], v[100:101], v[158:159] op_sel_hi:[1,0,1]
	v_pk_fma_f32 v[118:119], v[118:119], v[102:103], v[106:107] op_sel_hi:[1,0,1]
	v_pk_fma_f32 v[120:121], v[120:121], v[102:103], v[108:109] op_sel_hi:[1,0,1]
	v_pk_fma_f32 v[114:115], v[114:115], v[104:105], v[110:111] op_sel_hi:[1,0,1]
	v_pk_fma_f32 v[116:117], v[116:117], v[104:105], v[112:113] op_sel_hi:[1,0,1]
	global_store_dword v164, v134, s[100:101]
	global_store_dword v165, v135, s[100:101]
	global_store_dword v166, v136, s[100:101]
	global_store_dword v167, v137, s[100:101]
	global_store_dword v164, v130, s[100:101] offset:64
	global_store_dword v165, v131, s[100:101] offset:64
	global_store_dword v166, v132, s[100:101] offset:64
	global_store_dword v167, v133, s[100:101] offset:64
	global_store_dword v164, v118, s[100:101] offset:512
	global_store_dword v165, v119, s[100:101] offset:512
	global_store_dword v166, v120, s[100:101] offset:512
	global_store_dword v167, v121, s[100:101] offset:512
	global_store_dword v164, v114, s[100:101] offset:576
	global_store_dword v165, v115, s[100:101] offset:576
	global_store_dword v166, v116, s[100:101] offset:576
	global_store_dword v167, v117, s[100:101] offset:576
	s_add_u32 s100, s100, 0x20000
	s_addc_u32 s101, s101, 0
	global_load_dword v152, v164, s[98:99]
	global_load_dword v153, v165, s[98:99]
	global_load_dword v154, v166, s[98:99]
	global_load_dword v155, v167, s[98:99]
	global_load_dword v156, v164, s[98:99] offset:64
	global_load_dword v157, v165, s[98:99] offset:64
	global_load_dword v158, v166, s[98:99] offset:64
	global_load_dword v159, v167, s[98:99] offset:64
	global_load_dword v106, v164, s[98:99] offset:512
	global_load_dword v107, v165, s[98:99] offset:512
	global_load_dword v108, v166, s[98:99] offset:512
	global_load_dword v109, v167, s[98:99] offset:512
	global_load_dword v110, v164, s[98:99] offset:576
	global_load_dword v111, v165, s[98:99] offset:576
	global_load_dword v112, v166, s[98:99] offset:576
	global_load_dword v113, v167, s[98:99] offset:576
	s_add_u32 s98, s98, 0xa0000
	s_addc_u32 s99, s99, 0
	s_waitcnt vmcnt(32)
	v_pk_fma_f32 v[94:95], v[94:95], v[98:99], v[190:191] op_sel_hi:[1,0,1]
	v_pk_fma_f32 v[96:97], v[96:97], v[98:99], v[192:193] op_sel_hi:[1,0,1]
	v_pk_fma_f32 v[90:91], v[90:91], v[100:101], v[194:195] op_sel_hi:[1,0,1]
	v_pk_fma_f32 v[92:93], v[92:93], v[100:101], v[196:197] op_sel_hi:[1,0,1]
	v_pk_fma_f32 v[78:79], v[78:79], v[102:103], v[198:199] op_sel_hi:[1,0,1]
	v_pk_fma_f32 v[80:81], v[80:81], v[102:103], v[200:201] op_sel_hi:[1,0,1]
	v_pk_fma_f32 v[74:75], v[74:75], v[104:105], v[202:203] op_sel_hi:[1,0,1]
	v_pk_fma_f32 v[76:77], v[76:77], v[104:105], v[204:205] op_sel_hi:[1,0,1]
	global_store_dword v164, v94, s[100:101]
	global_store_dword v165, v95, s[100:101]
	global_store_dword v166, v96, s[100:101]
	global_store_dword v167, v97, s[100:101]
	global_store_dword v164, v90, s[100:101] offset:64
	global_store_dword v165, v91, s[100:101] offset:64
	global_store_dword v166, v92, s[100:101] offset:64
	global_store_dword v167, v93, s[100:101] offset:64
	global_store_dword v164, v78, s[100:101] offset:512
	global_store_dword v165, v79, s[100:101] offset:512
	global_store_dword v166, v80, s[100:101] offset:512
	global_store_dword v167, v81, s[100:101] offset:512
	global_store_dword v164, v74, s[100:101] offset:576
	global_store_dword v165, v75, s[100:101] offset:576
	global_store_dword v166, v76, s[100:101] offset:576
	global_store_dword v167, v77, s[100:101] offset:576
	s_add_u32 s100, s100, 0x20000
	s_addc_u32 s101, s101, 0
	global_load_dword v190, v164, s[98:99]
	global_load_dword v191, v165, s[98:99]
	global_load_dword v192, v166, s[98:99]
	global_load_dword v193, v167, s[98:99]
	global_load_dword v194, v164, s[98:99] offset:64
	global_load_dword v195, v165, s[98:99] offset:64
	global_load_dword v196, v166, s[98:99] offset:64
	global_load_dword v197, v167, s[98:99] offset:64
	global_load_dword v198, v164, s[98:99] offset:512
	global_load_dword v199, v165, s[98:99] offset:512
	global_load_dword v200, v166, s[98:99] offset:512
	global_load_dword v201, v167, s[98:99] offset:512
	global_load_dword v202, v164, s[98:99] offset:576
	global_load_dword v203, v165, s[98:99] offset:576
	global_load_dword v204, v166, s[98:99] offset:576
	global_load_dword v205, v167, s[98:99] offset:576
	s_add_u32 s98, s98, 0x20000
	s_addc_u32 s99, s99, 0
	s_waitcnt vmcnt(32)
	v_pk_fma_f32 v[86:87], v[86:87], v[98:99], v[152:153] op_sel_hi:[1,0,1]
	v_pk_fma_f32 v[88:89], v[88:89], v[98:99], v[154:155] op_sel_hi:[1,0,1]
	v_pk_fma_f32 v[82:83], v[82:83], v[100:101], v[156:157] op_sel_hi:[1,0,1]
	v_pk_fma_f32 v[84:85], v[84:85], v[100:101], v[158:159] op_sel_hi:[1,0,1]
	v_pk_fma_f32 v[70:71], v[70:71], v[102:103], v[106:107] op_sel_hi:[1,0,1]
	v_pk_fma_f32 v[72:73], v[72:73], v[102:103], v[108:109] op_sel_hi:[1,0,1]
	v_pk_fma_f32 v[66:67], v[66:67], v[104:105], v[110:111] op_sel_hi:[1,0,1]
	v_pk_fma_f32 v[68:69], v[68:69], v[104:105], v[112:113] op_sel_hi:[1,0,1]
	global_store_dword v164, v86, s[100:101]
	global_store_dword v165, v87, s[100:101]
	global_store_dword v166, v88, s[100:101]
	global_store_dword v167, v89, s[100:101]
	global_store_dword v164, v82, s[100:101] offset:64
	global_store_dword v165, v83, s[100:101] offset:64
	global_store_dword v166, v84, s[100:101] offset:64
	global_store_dword v167, v85, s[100:101] offset:64
	global_store_dword v164, v70, s[100:101] offset:512
	global_store_dword v165, v71, s[100:101] offset:512
	global_store_dword v166, v72, s[100:101] offset:512
	global_store_dword v167, v73, s[100:101] offset:512
	global_store_dword v164, v66, s[100:101] offset:576
	global_store_dword v165, v67, s[100:101] offset:576
	global_store_dword v166, v68, s[100:101] offset:576
	global_store_dword v167, v69, s[100:101] offset:576
	s_add_u32 s100, s100, 0xa0000
	s_addc_u32 s101, s101, 0
	global_load_dword v152, v164, s[98:99]
	global_load_dword v153, v165, s[98:99]
	global_load_dword v154, v166, s[98:99]
	global_load_dword v155, v167, s[98:99]
	global_load_dword v156, v164, s[98:99] offset:64
	global_load_dword v157, v165, s[98:99] offset:64
	global_load_dword v158, v166, s[98:99] offset:64
	global_load_dword v159, v167, s[98:99] offset:64
	global_load_dword v106, v164, s[98:99] offset:512
	global_load_dword v107, v165, s[98:99] offset:512
	global_load_dword v108, v166, s[98:99] offset:512
	global_load_dword v109, v167, s[98:99] offset:512
	global_load_dword v110, v164, s[98:99] offset:576
	global_load_dword v111, v165, s[98:99] offset:576
	global_load_dword v112, v166, s[98:99] offset:576
	global_load_dword v113, v167, s[98:99] offset:576
	s_add_u32 s98, s98, 0x20000
	s_addc_u32 s99, s99, 0
	s_waitcnt vmcnt(32)
	v_pk_fma_f32 v[62:63], v[62:63], v[98:99], v[190:191] op_sel_hi:[1,0,1]
	v_pk_fma_f32 v[64:65], v[64:65], v[98:99], v[192:193] op_sel_hi:[1,0,1]
	v_pk_fma_f32 v[58:59], v[58:59], v[100:101], v[194:195] op_sel_hi:[1,0,1]
	v_pk_fma_f32 v[60:61], v[60:61], v[100:101], v[196:197] op_sel_hi:[1,0,1]
	v_pk_fma_f32 v[46:47], v[46:47], v[102:103], v[198:199] op_sel_hi:[1,0,1]
	v_pk_fma_f32 v[48:49], v[48:49], v[102:103], v[200:201] op_sel_hi:[1,0,1]
	v_pk_fma_f32 v[42:43], v[42:43], v[104:105], v[202:203] op_sel_hi:[1,0,1]
	v_pk_fma_f32 v[44:45], v[44:45], v[104:105], v[204:205] op_sel_hi:[1,0,1]
	global_store_dword v164, v62, s[100:101]
	global_store_dword v165, v63, s[100:101]
	global_store_dword v166, v64, s[100:101]
	global_store_dword v167, v65, s[100:101]
	global_store_dword v164, v58, s[100:101] offset:64
	global_store_dword v165, v59, s[100:101] offset:64
	global_store_dword v166, v60, s[100:101] offset:64
	global_store_dword v167, v61, s[100:101] offset:64
	global_store_dword v164, v46, s[100:101] offset:512
	global_store_dword v165, v47, s[100:101] offset:512
	global_store_dword v166, v48, s[100:101] offset:512
	global_store_dword v167, v49, s[100:101] offset:512
	global_store_dword v164, v42, s[100:101] offset:576
	global_store_dword v165, v43, s[100:101] offset:576
	global_store_dword v166, v44, s[100:101] offset:576
	global_store_dword v167, v45, s[100:101] offset:576
	s_add_u32 s100, s100, 0x20000
	s_addc_u32 s101, s101, 0
	global_load_dword v190, v164, s[98:99]
	global_load_dword v191, v165, s[98:99]
	global_load_dword v192, v166, s[98:99]
	global_load_dword v193, v167, s[98:99]
	global_load_dword v194, v164, s[98:99] offset:64
	global_load_dword v195, v165, s[98:99] offset:64
	global_load_dword v196, v166, s[98:99] offset:64
	global_load_dword v197, v167, s[98:99] offset:64
	global_load_dword v198, v164, s[98:99] offset:512
	global_load_dword v199, v165, s[98:99] offset:512
	global_load_dword v200, v166, s[98:99] offset:512
	global_load_dword v201, v167, s[98:99] offset:512
	global_load_dword v202, v164, s[98:99] offset:576
	global_load_dword v203, v165, s[98:99] offset:576
	global_load_dword v204, v166, s[98:99] offset:576
	global_load_dword v205, v167, s[98:99] offset:576
	s_add_u32 s98, s98, 0x20000
	s_addc_u32 s99, s99, 0
	s_waitcnt vmcnt(32)
	v_pk_fma_f32 v[54:55], v[54:55], v[98:99], v[152:153] op_sel_hi:[1,0,1]
	v_pk_fma_f32 v[56:57], v[56:57], v[98:99], v[154:155] op_sel_hi:[1,0,1]
	v_pk_fma_f32 v[50:51], v[50:51], v[100:101], v[156:157] op_sel_hi:[1,0,1]
	v_pk_fma_f32 v[52:53], v[52:53], v[100:101], v[158:159] op_sel_hi:[1,0,1]
	v_pk_fma_f32 v[38:39], v[38:39], v[102:103], v[106:107] op_sel_hi:[1,0,1]
	v_pk_fma_f32 v[40:41], v[40:41], v[102:103], v[108:109] op_sel_hi:[1,0,1]
	v_pk_fma_f32 v[34:35], v[34:35], v[104:105], v[110:111] op_sel_hi:[1,0,1]
	v_pk_fma_f32 v[36:37], v[36:37], v[104:105], v[112:113] op_sel_hi:[1,0,1]
	global_store_dword v164, v54, s[100:101]
	global_store_dword v165, v55, s[100:101]
	global_store_dword v166, v56, s[100:101]
	global_store_dword v167, v57, s[100:101]
	global_store_dword v164, v50, s[100:101] offset:64
	global_store_dword v165, v51, s[100:101] offset:64
	global_store_dword v166, v52, s[100:101] offset:64
	global_store_dword v167, v53, s[100:101] offset:64
	global_store_dword v164, v38, s[100:101] offset:512
	global_store_dword v165, v39, s[100:101] offset:512
	global_store_dword v166, v40, s[100:101] offset:512
	global_store_dword v167, v41, s[100:101] offset:512
	global_store_dword v164, v34, s[100:101] offset:576
	global_store_dword v165, v35, s[100:101] offset:576
	global_store_dword v166, v36, s[100:101] offset:576
	global_store_dword v167, v37, s[100:101] offset:576
	s_add_u32 s100, s100, 0x20000
	s_addc_u32 s101, s101, 0
	global_load_dword v152, v164, s[98:99]
	global_load_dword v153, v165, s[98:99]
	global_load_dword v154, v166, s[98:99]
	global_load_dword v155, v167, s[98:99]
	global_load_dword v156, v164, s[98:99] offset:64
	global_load_dword v157, v165, s[98:99] offset:64
	global_load_dword v158, v166, s[98:99] offset:64
	global_load_dword v159, v167, s[98:99] offset:64
	global_load_dword v106, v164, s[98:99] offset:512
	global_load_dword v107, v165, s[98:99] offset:512
	global_load_dword v108, v166, s[98:99] offset:512
	global_load_dword v109, v167, s[98:99] offset:512
	global_load_dword v110, v164, s[98:99] offset:576
	global_load_dword v111, v165, s[98:99] offset:576
	global_load_dword v112, v166, s[98:99] offset:576
	global_load_dword v113, v167, s[98:99] offset:576
	s_waitcnt vmcnt(32)
	v_pk_fma_f32 v[28:29], v[28:29], v[98:99], v[190:191] op_sel_hi:[1,0,1]
	v_pk_fma_f32 v[30:31], v[30:31], v[98:99], v[192:193] op_sel_hi:[1,0,1]
	v_pk_fma_f32 v[24:25], v[24:25], v[100:101], v[194:195] op_sel_hi:[1,0,1]
	v_pk_fma_f32 v[26:27], v[26:27], v[100:101], v[196:197] op_sel_hi:[1,0,1]
	v_pk_fma_f32 v[12:13], v[12:13], v[102:103], v[198:199] op_sel_hi:[1,0,1]
	v_pk_fma_f32 v[14:15], v[14:15], v[102:103], v[200:201] op_sel_hi:[1,0,1]
	v_pk_fma_f32 v[8:9], v[8:9], v[104:105], v[202:203] op_sel_hi:[1,0,1]
	v_pk_fma_f32 v[10:11], v[10:11], v[104:105], v[204:205] op_sel_hi:[1,0,1]
	global_store_dword v164, v28, s[100:101]
	global_store_dword v165, v29, s[100:101]
	global_store_dword v166, v30, s[100:101]
	global_store_dword v167, v31, s[100:101]
	global_store_dword v164, v24, s[100:101] offset:64
	global_store_dword v165, v25, s[100:101] offset:64
	global_store_dword v166, v26, s[100:101] offset:64
	global_store_dword v167, v27, s[100:101] offset:64
	global_store_dword v164, v12, s[100:101] offset:512
	global_store_dword v165, v13, s[100:101] offset:512
	global_store_dword v166, v14, s[100:101] offset:512
	global_store_dword v167, v15, s[100:101] offset:512
	global_store_dword v164, v8, s[100:101] offset:576
	global_store_dword v165, v9, s[100:101] offset:576
	global_store_dword v166, v10, s[100:101] offset:576
	global_store_dword v167, v11, s[100:101] offset:576
	s_add_u32 s100, s100, 0x20000
	s_addc_u32 s101, s101, 0
	s_waitcnt vmcnt(16)
	v_pk_fma_f32 v[20:21], v[20:21], v[98:99], v[152:153] op_sel_hi:[1,0,1]
	v_pk_fma_f32 v[22:23], v[22:23], v[98:99], v[154:155] op_sel_hi:[1,0,1]
	v_pk_fma_f32 v[16:17], v[16:17], v[100:101], v[156:157] op_sel_hi:[1,0,1]
	v_pk_fma_f32 v[18:19], v[18:19], v[100:101], v[158:159] op_sel_hi:[1,0,1]
	v_pk_fma_f32 v[4:5], v[4:5], v[102:103], v[106:107] op_sel_hi:[1,0,1]
	v_pk_fma_f32 v[6:7], v[6:7], v[102:103], v[108:109] op_sel_hi:[1,0,1]
	v_pk_fma_f32 v[0:1], v[0:1], v[104:105], v[110:111] op_sel_hi:[1,0,1]
	v_pk_fma_f32 v[2:3], v[2:3], v[104:105], v[112:113] op_sel_hi:[1,0,1]
	global_store_dword v164, v20, s[100:101]
	global_store_dword v165, v21, s[100:101]
	global_store_dword v166, v22, s[100:101]
	global_store_dword v167, v23, s[100:101]
	global_store_dword v164, v16, s[100:101] offset:64
	global_store_dword v165, v17, s[100:101] offset:64
	global_store_dword v166, v18, s[100:101] offset:64
	global_store_dword v167, v19, s[100:101] offset:64
	global_store_dword v164, v4, s[100:101] offset:512
	global_store_dword v165, v5, s[100:101] offset:512
	global_store_dword v166, v6, s[100:101] offset:512
	global_store_dword v167, v7, s[100:101] offset:512
	global_store_dword v164, v0, s[100:101] offset:576
	global_store_dword v165, v1, s[100:101] offset:576
	global_store_dword v166, v2, s[100:101] offset:576
	global_store_dword v167, v3, s[100:101] offset:576
	s_mov_b64 s[14:15], -1
	s_andn2_b64 vcc, exec, s[2:3]
	s_cbranch_vccnz .LBB0_860
	s_andn2_b64 vcc, exec, s[0:1]
	s_cbranch_vccnz .LBB0_859
	s_barrier
	s_branch .LBB0_859
